# SWA too: O accumulated transposed, lane-local rescale / sink / 1/l, 4 dwordx4 row stores instead of 32 two-byte stores per lane
# baseline (speedup 1.0000x reference)
.Lswa_prio_done:
	v_mov_b32_e32 v159, v117
	v_exp_f32_e32 v32, v48
	v_exp_f32_e32 v33, v49
	v_exp_f32_e32 v34, v34
	v_exp_f32_e32 v35, v35
	v_exp_f32_e32 v36, v36
	v_exp_f32_e32 v37, v37
	v_exp_f32_e32 v38, v38
	v_exp_f32_e32 v39, v39
	v_exp_f32_e32 v40, v40
	v_exp_f32_e32 v41, v41
	v_exp_f32_e32 v42, v42
	v_exp_f32_e32 v43, v43
	v_exp_f32_e32 v44, v44
	v_exp_f32_e32 v45, v45
	v_exp_f32_e32 v46, v46
	v_exp_f32_e32 v47, v47
	v_add_f32_e32 v155, 0, v63
	v_add_f32_e32 v155, v82, v155
	v_add_f32_e32 v155, v61, v155
	v_add_f32_e32 v155, v81, v155
	v_add_f32_e32 v155, v59, v155
	v_add_f32_e32 v155, v62, v155
	v_add_f32_e32 v155, v58, v155
	v_add_f32_e32 v155, v60, v155
	v_add_f32_e32 v155, v55, v155
	v_add_f32_e32 v155, v57, v155
	v_add_f32_e32 v155, v53, v155
	v_add_f32_e32 v155, v56, v155
	v_add_f32_e32 v155, v51, v155
	v_add_f32_e32 v155, v54, v155
	v_add_f32_e32 v155, v50, v155
	v_add_f32_e32 v155, v52, v155
	v_add_f32_e32 v155, v32, v155
	v_add_f32_e32 v155, v33, v155
	v_add_f32_e32 v155, v34, v155
	v_add_f32_e32 v155, v35, v155
	v_add_f32_e32 v155, v36, v155
	v_add_f32_e32 v155, v37, v155
	v_add_f32_e32 v155, v38, v155
	v_add_f32_e32 v155, v39, v155
	v_add_f32_e32 v155, v40, v155
	v_add_f32_e32 v155, v41, v155
	v_add_f32_e32 v155, v42, v155
	v_add_f32_e32 v155, v43, v155
	v_add_f32_e32 v155, v44, v155
	v_add_f32_e32 v155, v45, v155
	v_add_f32_e32 v155, v46, v155
	v_add_f32_e32 v155, v47, v155
	v_mov_b32_e32 v156, v155
	v_cvt_pk_bf16_f32 v80, v63, v82
	v_cvt_pk_bf16_f32 v81, v61, v81
	v_cvt_pk_bf16_f32 v82, v59, v62
	v_cvt_pk_bf16_f32 v83, v58, v60
	v_cvt_pk_bf16_f32 v84, v55, v57
	v_cvt_pk_bf16_f32 v85, v53, v56
	v_cvt_pk_bf16_f32 v86, v51, v54
	v_cvt_pk_bf16_f32 v87, v50, v52
	v_cvt_pk_bf16_f32 v88, v32, v33
	v_cvt_pk_bf16_f32 v89, v34, v35
	v_cvt_pk_bf16_f32 v90, v36, v37
	v_cvt_pk_bf16_f32 v91, v38, v39
	v_cvt_pk_bf16_f32 v92, v40, v41
	v_cvt_pk_bf16_f32 v93, v42, v43
	v_cvt_pk_bf16_f32 v94, v44, v45
	v_cvt_pk_bf16_f32 v95, v46, v47
	v_permlane32_swap_b32_e32 v155, v156
	v_add_f32_e32 v157, v155, v156
	v_fma_f32 v108, v114, v108, v157
	v_permlane32_swap_b32_e32 v80, v82
	v_permlane32_swap_b32_e32 v81, v83
	v_permlane32_swap_b32_e32 v84, v86
	v_permlane32_swap_b32_e32 v85, v87
	v_permlane32_swap_b32_e32 v88, v90
	v_permlane32_swap_b32_e32 v89, v91
	v_permlane32_swap_b32_e32 v92, v94
	v_permlane32_swap_b32_e32 v93, v95
	ds_read_b64_tr_b16 v[120:121], v109 offset:0
	ds_read_b64_tr_b16 v[122:123], v109 offset:1024
	ds_read_b64_tr_b16 v[124:125], v109 offset:2048
	ds_read_b64_tr_b16 v[126:127], v109 offset:3072
	ds_read_b64_tr_b16 v[128:129], v109 offset:4096
	ds_read_b64_tr_b16 v[130:131], v109 offset:5120
	ds_read_b64_tr_b16 v[132:133], v109 offset:6144
	ds_read_b64_tr_b16 v[134:135], v109 offset:7168
	ds_read_b64_tr_b16 v[136:137], v109 offset:512
	ds_read_b64_tr_b16 v[138:139], v109 offset:1536
	ds_read_b64_tr_b16 v[140:141], v109 offset:2560
	ds_read_b64_tr_b16 v[142:143], v109 offset:3584
	ds_read_b64_tr_b16 v[144:145], v109 offset:4608
	ds_read_b64_tr_b16 v[146:147], v109 offset:5632
	ds_read_b64_tr_b16 v[148:149], v109 offset:6656
	ds_read_b64_tr_b16 v[150:151], v109 offset:7680
	s_waitcnt lgkmcnt(0)
	v_mfma_f32_32x32x16_bf16 v[16:31], v[120:123], v[80:83], v[16:31]
	v_mfma_f32_32x32x16_bf16 v[16:31], v[124:127], v[84:87], v[16:31]
	v_mfma_f32_32x32x16_bf16 v[16:31], v[128:131], v[88:91], v[16:31]
	v_mfma_f32_32x32x16_bf16 v[16:31], v[132:135], v[92:95], v[16:31]
	v_mfma_f32_32x32x16_bf16 v[0:15], v[136:139], v[80:83], v[0:15]
	v_mfma_f32_32x32x16_bf16 v[0:15], v[140:143], v[84:87], v[0:15]
	v_mfma_f32_32x32x16_bf16 v[0:15], v[144:147], v[88:91], v[0:15]
	v_mfma_f32_32x32x16_bf16 v[0:15], v[148:151], v[92:95], v[0:15]
	s_waitcnt vmcnt(0) lgkmcnt(0)
	s_barrier

.Lswa_nomask_o:
	v_max_f32_e32 v152, v48, v49
	v_max3_f32 v152, v152, v50, v51
	v_max3_f32 v152, v152, v52, v53
	v_max3_f32 v152, v152, v54, v55
	v_max3_f32 v152, v152, v56, v57
	v_max3_f32 v152, v152, v58, v59
	v_max3_f32 v152, v152, v60, v61
	v_max3_f32 v152, v152, v62, v63
	v_max3_f32 v152, v152, v32, v33
	v_max3_f32 v152, v152, v34, v35
	v_max3_f32 v152, v152, v36, v37
	v_max3_f32 v152, v152, v38, v39
	v_max3_f32 v152, v152, v40, v41
	v_max3_f32 v152, v152, v42, v43
	v_max3_f32 v152, v152, v44, v45
	v_max3_f32 v152, v152, v46, v47
	v_mov_b32_e32 v153, v152
	s_nop 1
	v_permlane32_swap_b32_e32 v152, v153
	v_max_f32_e32 v152, v152, v153
	v_sub_f32_e32 v153, v152, v115
	v_cmp_ge_f32_e32 vcc, s41, v153
	v_max_f32_e32 v152, v115, v152
	v_sub_f32_e32 v153, v115, v152
	v_mul_f32_e32 v153, 0x3e38aa3b, v153
	v_exp_f32_e32 v153, v153
	s_cmp_eq_u64 vcc, exec
	s_cselect_b64 s[10:11], -1, 0
	v_cndmask_b32_e64 v114, v153, 1.0, s[10:11]
	v_cndmask_b32_e64 v115, v152, v115, s[10:11]
	v_mul_f32_e32 v154, 0xbe38aa3b, v115
	v_fmamk_f32 v48, v48, 0x3e38aa3b, v154
	v_fmamk_f32 v49, v49, 0x3e38aa3b, v154
	v_fmamk_f32 v50, v50, 0x3e38aa3b, v154
	v_fmamk_f32 v51, v51, 0x3e38aa3b, v154
	v_fmamk_f32 v52, v52, 0x3e38aa3b, v154
	v_fmamk_f32 v53, v53, 0x3e38aa3b, v154
	v_fmamk_f32 v54, v54, 0x3e38aa3b, v154
	v_fmamk_f32 v55, v55, 0x3e38aa3b, v154
	v_fmamk_f32 v56, v56, 0x3e38aa3b, v154
	v_fmamk_f32 v57, v57, 0x3e38aa3b, v154
	v_fmamk_f32 v58, v58, 0x3e38aa3b, v154
	v_fmamk_f32 v59, v59, 0x3e38aa3b, v154
	v_fmamk_f32 v60, v60, 0x3e38aa3b, v154
	v_fmamk_f32 v61, v61, 0x3e38aa3b, v154
	v_fmamk_f32 v62, v62, 0x3e38aa3b, v154
	v_fmamk_f32 v63, v63, 0x3e38aa3b, v154
	v_fmamk_f32 v32, v32, 0x3e38aa3b, v154
	v_fmamk_f32 v33, v33, 0x3e38aa3b, v154
	v_fmamk_f32 v34, v34, 0x3e38aa3b, v154
	v_fmamk_f32 v35, v35, 0x3e38aa3b, v154
	v_fmamk_f32 v36, v36, 0x3e38aa3b, v154
	v_fmamk_f32 v37, v37, 0x3e38aa3b, v154
	v_fmamk_f32 v38, v38, 0x3e38aa3b, v154
	v_fmamk_f32 v39, v39, 0x3e38aa3b, v154
	v_fmamk_f32 v40, v40, 0x3e38aa3b, v154
	v_fmamk_f32 v41, v41, 0x3e38aa3b, v154
	v_fmamk_f32 v42, v42, 0x3e38aa3b, v154
	v_fmamk_f32 v43, v43, 0x3e38aa3b, v154
	v_fmamk_f32 v44, v44, 0x3e38aa3b, v154
	v_fmamk_f32 v45, v45, 0x3e38aa3b, v154
	v_fmamk_f32 v46, v46, 0x3e38aa3b, v154
	v_fmamk_f32 v47, v47, 0x3e38aa3b, v154
	v_exp_f32_e32 v48, v48
	v_exp_f32_e32 v49, v49
	v_add_f32_e32 v155, 0, v48
	v_exp_f32_e32 v50, v50
	v_add_f32_e32 v155, v49, v155
	v_exp_f32_e32 v51, v51
	v_add_f32_e32 v155, v50, v155
	v_exp_f32_e32 v52, v52
	v_add_f32_e32 v155, v51, v155
	v_exp_f32_e32 v53, v53
	v_add_f32_e32 v155, v52, v155
	v_exp_f32_e32 v54, v54
	v_add_f32_e32 v155, v53, v155
	v_exp_f32_e32 v55, v55
	v_add_f32_e32 v155, v54, v155
	v_exp_f32_e32 v56, v56
	v_add_f32_e32 v155, v55, v155
	v_exp_f32_e32 v57, v57
	v_add_f32_e32 v155, v56, v155
	v_exp_f32_e32 v58, v58
	v_add_f32_e32 v155, v57, v155
	v_exp_f32_e32 v59, v59
	v_add_f32_e32 v155, v58, v155
	v_exp_f32_e32 v60, v60
	v_add_f32_e32 v155, v59, v155
	v_exp_f32_e32 v61, v61
	v_add_f32_e32 v155, v60, v155
	v_exp_f32_e32 v62, v62
	v_add_f32_e32 v155, v61, v155
	v_exp_f32_e32 v63, v63
	v_add_f32_e32 v155, v62, v155
	v_exp_f32_e32 v32, v32
	v_add_f32_e32 v155, v63, v155
	v_exp_f32_e32 v33, v33
	v_add_f32_e32 v155, v32, v155
	v_exp_f32_e32 v34, v34
	v_add_f32_e32 v155, v33, v155
	v_exp_f32_e32 v35, v35
	v_add_f32_e32 v155, v34, v155
	v_exp_f32_e32 v36, v36
	v_add_f32_e32 v155, v35, v155
	v_exp_f32_e32 v37, v37
	v_add_f32_e32 v155, v36, v155
	v_exp_f32_e32 v38, v38
	v_add_f32_e32 v155, v37, v155
	v_exp_f32_e32 v39, v39
	v_add_f32_e32 v155, v38, v155
	v_exp_f32_e32 v40, v40
	v_add_f32_e32 v155, v39, v155
	v_exp_f32_e32 v41, v41
	v_add_f32_e32 v155, v40, v155
	v_exp_f32_e32 v42, v42
	v_add_f32_e32 v155, v41, v155
	v_exp_f32_e32 v43, v43
	v_add_f32_e32 v155, v42, v155
	v_exp_f32_e32 v44, v44
	v_add_f32_e32 v155, v43, v155
	v_exp_f32_e32 v45, v45
	v_add_f32_e32 v155, v44, v155
	v_exp_f32_e32 v46, v46
	v_add_f32_e32 v155, v45, v155
	v_exp_f32_e32 v47, v47
	v_add_f32_e32 v155, v46, v155
	s_nop 0
	v_add_f32_e32 v155, v47, v155
	v_mov_b32_e32 v156, v155
	v_cvt_pk_bf16_f32 v80, v48, v49
	v_cvt_pk_bf16_f32 v81, v50, v51
	v_cvt_pk_bf16_f32 v82, v52, v53
	v_cvt_pk_bf16_f32 v83, v54, v55
	v_cvt_pk_bf16_f32 v84, v56, v57
	v_cvt_pk_bf16_f32 v85, v58, v59
	v_cvt_pk_bf16_f32 v86, v60, v61
	v_cvt_pk_bf16_f32 v87, v62, v63
	v_cvt_pk_bf16_f32 v88, v32, v33
	v_cvt_pk_bf16_f32 v89, v34, v35
	v_cvt_pk_bf16_f32 v90, v36, v37
	v_cvt_pk_bf16_f32 v91, v38, v39
	v_cvt_pk_bf16_f32 v92, v40, v41
	v_cvt_pk_bf16_f32 v93, v42, v43
	v_cvt_pk_bf16_f32 v94, v44, v45
	v_cvt_pk_bf16_f32 v95, v46, v47
	v_permlane32_swap_b32_e32 v155, v156
	v_add_f32_e32 v157, v155, v156
	v_fma_f32 v108, v114, v108, v157
	v_permlane32_swap_b32_e32 v80, v82
	v_permlane32_swap_b32_e32 v81, v83
	v_permlane32_swap_b32_e32 v84, v86
	v_permlane32_swap_b32_e32 v85, v87
	v_permlane32_swap_b32_e32 v88, v90
	v_permlane32_swap_b32_e32 v89, v91
	v_permlane32_swap_b32_e32 v92, v94
	v_permlane32_swap_b32_e32 v93, v95
	v_cmp_gt_f32_e32 vcc, 1.0, v114
	s_cbranch_vccz .Lswa_noresc_o
	v_mul_f32_e32 v16, v114, v16
	v_mul_f32_e32 v17, v114, v17
	v_mul_f32_e32 v18, v114, v18
	v_mul_f32_e32 v19, v114, v19
	v_mul_f32_e32 v20, v114, v20
	v_mul_f32_e32 v21, v114, v21
	v_mul_f32_e32 v22, v114, v22
	v_mul_f32_e32 v23, v114, v23
	v_mul_f32_e32 v24, v114, v24
	v_mul_f32_e32 v25, v114, v25
	v_mul_f32_e32 v26, v114, v26
	v_mul_f32_e32 v27, v114, v27
	v_mul_f32_e32 v28, v114, v28
	v_mul_f32_e32 v29, v114, v29
	v_mul_f32_e32 v30, v114, v30
	v_mul_f32_e32 v31, v114, v31
	v_mul_f32_e32 v0, v114, v0
	v_mul_f32_e32 v1, v114, v1
	v_mul_f32_e32 v2, v114, v2
	v_mul_f32_e32 v3, v114, v3
	v_mul_f32_e32 v4, v114, v4
	v_mul_f32_e32 v5, v114, v5
	v_mul_f32_e32 v6, v114, v6
	v_mul_f32_e32 v7, v114, v7
	v_mul_f32_e32 v8, v114, v8
	v_mul_f32_e32 v9, v114, v9
	v_mul_f32_e32 v10, v114, v10
	v_mul_f32_e32 v11, v114, v11
	v_mul_f32_e32 v12, v114, v12
	v_mul_f32_e32 v13, v114, v13
	v_mul_f32_e32 v14, v114, v14
	v_mul_f32_e32 v15, v114, v15
	s_nop 1
.Lswa_noresc_o:
	s_waitcnt lgkmcnt(0)
	v_mfma_f32_32x32x16_bf16 v[16:31], v[120:123], v[80:83], v[16:31]
	v_mfma_f32_32x32x16_bf16 v[16:31], v[124:127], v[84:87], v[16:31]
	v_mfma_f32_32x32x16_bf16 v[16:31], v[128:131], v[88:91], v[16:31]
	v_mfma_f32_32x32x16_bf16 v[16:31], v[132:135], v[92:95], v[16:31]
	v_mfma_f32_32x32x16_bf16 v[0:15], v[136:139], v[80:83], v[0:15]
	v_mfma_f32_32x32x16_bf16 v[0:15], v[140:143], v[84:87], v[0:15]
	v_mfma_f32_32x32x16_bf16 v[0:15], v[144:147], v[88:91], v[0:15]
	v_mfma_f32_32x32x16_bf16 v[0:15], v[148:151], v[92:95], v[0:15]

.Lswa_done:
	s_setprio 0
	v_mul_f32_e32 v156, 0x3fb8aa3b, v96
	v_mul_f32_e32 v157, 0x3e38aa3b, v115
	v_sub_f32_e32 v156, v156, v157
	v_exp_f32_e32 v156, v156
	v_cmp_gt_u32_e32 vcc, 32, v105
	s_nop 0
	v_add_f32_e32 v156, v156, v108
	s_ashr_i32 s7, s6, 31
	s_lshl_b64 s[0:1], s[6:7], 12
	s_add_u32 s0, s4, s0
	s_addc_u32 s1, s5, s1
	v_rcp_f32_e32 v157, v156
	v_lshlrev_b32_e32 v160, 12, v102
	v_lshl_add_u32 v160, v103, 4, v160
	s_nop 1
	v_lshl_add_u64 v[250:251], s[0:1], 0, v[160:161]
	v_mul_f32_e32 v16, v157, v16
	v_mul_f32_e32 v17, v157, v17
	v_mul_f32_e32 v18, v157, v18
	v_mul_f32_e32 v19, v157, v19
	v_mul_f32_e32 v20, v157, v20
	v_mul_f32_e32 v21, v157, v21
	v_mul_f32_e32 v22, v157, v22
	v_mul_f32_e32 v23, v157, v23
	v_mul_f32_e32 v24, v157, v24
	v_mul_f32_e32 v25, v157, v25
	v_mul_f32_e32 v26, v157, v26
	v_mul_f32_e32 v27, v157, v27
	v_mul_f32_e32 v28, v157, v28
	v_mul_f32_e32 v29, v157, v29
	v_mul_f32_e32 v30, v157, v30
	v_mul_f32_e32 v31, v157, v31
	v_cvt_pk_bf16_f32 v16, v16, v17
	v_cvt_pk_bf16_f32 v17, v18, v19
	v_cvt_pk_bf16_f32 v18, v20, v21
	v_cvt_pk_bf16_f32 v19, v22, v23
	v_cvt_pk_bf16_f32 v20, v24, v25
	v_cvt_pk_bf16_f32 v21, v26, v27
	v_cvt_pk_bf16_f32 v22, v28, v29
	v_cvt_pk_bf16_f32 v23, v30, v31
	s_nop 1
	v_permlane32_swap_b32_e32 v16, v18
	v_permlane32_swap_b32_e32 v17, v19
	v_permlane32_swap_b32_e32 v20, v22
	v_permlane32_swap_b32_e32 v21, v23
	global_store_dwordx4 v[250:251], v[16:19], off
	global_store_dwordx4 v[250:251], v[20:23], off offset:32
	v_mul_f32_e32 v0, v157, v0
	v_mul_f32_e32 v1, v157, v1
	v_mul_f32_e32 v2, v157, v2
	v_mul_f32_e32 v3, v157, v3
	v_mul_f32_e32 v4, v157, v4
	v_mul_f32_e32 v5, v157, v5
	v_mul_f32_e32 v6, v157, v6
	v_mul_f32_e32 v7, v157, v7
	v_mul_f32_e32 v8, v157, v8
	v_mul_f32_e32 v9, v157, v9
	v_mul_f32_e32 v10, v157, v10
	v_mul_f32_e32 v11, v157, v11
	v_mul_f32_e32 v12, v157, v12
	v_mul_f32_e32 v13, v157, v13
	v_mul_f32_e32 v14, v157, v14
	v_mul_f32_e32 v15, v157, v15
	v_cvt_pk_bf16_f32 v0, v0, v1
	v_cvt_pk_bf16_f32 v1, v2, v3
	v_cvt_pk_bf16_f32 v2, v4, v5
	v_cvt_pk_bf16_f32 v3, v6, v7
	v_cvt_pk_bf16_f32 v4, v8, v9
	v_cvt_pk_bf16_f32 v5, v10, v11
	v_cvt_pk_bf16_f32 v6, v12, v13
	v_cvt_pk_bf16_f32 v7, v14, v15
	s_nop 1
	v_permlane32_swap_b32_e32 v0, v2
	v_permlane32_swap_b32_e32 v1, v3
	v_permlane32_swap_b32_e32 v4, v6
	v_permlane32_swap_b32_e32 v5, v7
	global_store_dwordx4 v[250:251], v[0:3], off offset:64
	global_store_dwordx4 v[250:251], v[4:7], off offset:96
	s_add_i32 s22, s22, s34
	s_waitcnt lgkmcnt(0)
	s_barrier
	s_cmp_ge_i32 s22, s14
	s_cbranch_scc1 .LBB0_546
	s_branch .LBB0_731
